# layer-3 decode attention loop: Q fragments kept in registers instead of per-iteration LDS reads, fp8->bf16 convert overlapped with MFMA, counted vmcnt so the next-chunk prefetch stays in flight, PV LD
# speedup vs baseline: 1.0114x; 1.0045x over previous
.LBB0_3809:
	s_lshl_b32 s1, s2, 14
	s_add_i32 s8, s1, 0
	s_ashr_i32 s1, s2, 31
	s_add_u32 s4, s46, s2
	s_addc_u32 s1, s47, s1
	s_mul_i32 s1, s1, 0x28000
	s_mul_hi_u32 s5, s4, 0x28000
	s_add_i32 s5, s5, s1
	s_mul_i32 s4, s4, 0x28000
	s_add_u32 s4, s93, s4
	s_addc_u32 s5, s94, s5
	v_lshlrev_b32_e32 v0, 3, v6
	s_waitcnt lgkmcnt(0)
	s_barrier
	global_load_dwordx2 v[74:75], v0, s[4:5]
	global_load_dwordx2 v[76:77], v0, s[4:5] offset:512
	global_load_dwordx2 v[78:79], v0, s[4:5] offset:1024
	global_load_dwordx2 v[80:81], v0, s[4:5] offset:1536
	global_load_dwordx2 v[82:83], v0, s[4:5] offset:2048
	global_load_dwordx2 v[84:85], v0, s[4:5] offset:2560
	global_load_dwordx2 v[86:87], v0, s[4:5] offset:3072
	global_load_dwordx2 v[88:89], v0, s[4:5] offset:3584
	v_lshl_add_u64 v[2:3], s[4:5], 0, v[0:1]
	v_add_co_u32_e32 v2, vcc, s70, v2
	v_lshrrev_b32_e32 v8, 4, v6
	s_nop 0
	v_addc_co_u32_e32 v3, vcc, 0, v3, vcc
	global_load_dwordx2 v[90:91], v[2:3], off
	global_load_dwordx2 v[92:93], v[2:3], off offset:512
	v_lshlrev_b32_e32 v2, 1, v7
	v_and_b32_e32 v3, 14, v2
	v_bitop3_b32 v2, v2, v8, 14 bitop3:0x6c
	v_lshrrev_b32_e32 v9, 2, v7
	v_lshl_add_u32 v10, v7, 9, s8
	v_lshlrev_b32_e32 v7, 4, v2
	v_bitop3_b32 v2, v8, v3, 4 bitop3:0x36
	v_lshlrev_b32_e32 v11, 4, v2
	v_bitop3_b32 v2, v8, v3, 8 bitop3:0x36
	v_lshlrev_b32_e32 v12, 4, v2
	v_bitop3_b32 v2, v8, v3, 12 bitop3:0x36
	v_lshlrev_b32_e32 v13, 4, v2
	v_bitop3_b32 v2, v8, v3, 16 bitop3:0x36
	v_lshlrev_b32_e32 v14, 4, v2
	v_bitop3_b32 v2, v8, v3, 20 bitop3:0x36
	v_lshlrev_b32_e32 v15, 4, v2
	v_bitop3_b32 v2, v8, v3, 24 bitop3:0x36
	v_lshlrev_b32_e32 v16, 4, v2
	v_bitop3_b32 v2, v8, v3, 28 bitop3:0x36
	v_lshlrev_b32_e32 v17, 4, v2
	v_lshlrev_b32_e32 v2, 2, v6
	v_xor_b32_e32 v114, 64, v2
	v_xor_b32_e32 v97, 0x80, v2
	v_lshl_or_b32 v2, v8, 2, v9
	v_lshlrev_b32_e32 v6, 1, v2
	v_bfe_u32 v3, v5, 1, 1
	v_and_b32_e32 v8, 14, v6
	v_or_b32_e32 v8, v8, v3
	v_or_b32_e32 v9, 2, v3
	v_or_b32_e32 v18, 4, v3
	v_or_b32_e32 v19, 6, v3
	v_or_b32_e32 v20, 8, v3
	v_or_b32_e32 v21, 10, v3
	v_or_b32_e32 v22, 12, v3
	v_bitop3_b32 v23, v6, v3, 14 bitop3:0x4e
	v_or_b32_e32 v24, v6, v3
	v_or_b32_e32 v25, 18, v3
	v_or_b32_e32 v26, 20, v3
	v_or_b32_e32 v27, 22, v3
	v_or_b32_e32 v28, 24, v3
	v_or_b32_e32 v29, 26, v3
	v_or_b32_e32 v30, 28, v3
	v_or_b32_e32 v3, 30, v3
	s_mul_hi_i32 s5, s2, 0x28000
	s_mul_i32 s2, s2, 0x28000
	v_lshlrev_b32_e32 v5, 3, v5
	v_lshl_add_u32 v2, v2, 9, s8
	v_bitop3_b32 v9, v6, v9, 14 bitop3:0x6c
	v_bitop3_b32 v18, v6, v18, 14 bitop3:0x6c
	v_bitop3_b32 v19, v6, v19, 14 bitop3:0x6c
	v_bitop3_b32 v20, v6, v20, 14 bitop3:0x6c
	v_bitop3_b32 v21, v6, v21, 14 bitop3:0x6c
	v_bitop3_b32 v22, v6, v22, 14 bitop3:0x6c
	v_lshl_or_b32 v24, v24, 4, v151
	v_bitop3_b32 v25, v6, v25, 14 bitop3:0x6c
	v_bitop3_b32 v26, v6, v26, 14 bitop3:0x6c
	v_bitop3_b32 v27, v6, v27, 14 bitop3:0x6c
	v_bitop3_b32 v28, v6, v28, 14 bitop3:0x6c
	v_bitop3_b32 v29, v6, v29, 14 bitop3:0x6c
	v_bitop3_b32 v30, v6, v30, 14 bitop3:0x6c
	v_bitop3_b32 v3, v6, v3, 14 bitop3:0x6c
	s_add_u32 s4, s95, s2
	v_and_b32_e32 v5, 8, v5
	v_lshl_add_u32 v8, v8, 4, v2
	v_lshl_add_u32 v9, v9, 4, v2
	v_lshl_add_u32 v18, v18, 4, v2
	v_lshl_add_u32 v19, v19, 4, v2
	v_lshl_add_u32 v20, v20, 4, v2
	v_lshl_add_u32 v21, v21, 4, v2
	v_lshl_add_u32 v22, v22, 4, v2
	v_lshl_add_u32 v23, v23, 4, v2
	v_add_u32_e32 v24, v2, v24
	v_lshl_add_u32 v25, v25, 4, v2
	v_lshl_add_u32 v26, v26, 4, v2
	v_lshl_add_u32 v27, v27, 4, v2
	v_lshl_add_u32 v28, v28, 4, v2
	v_lshl_add_u32 v29, v29, 4, v2
	v_lshl_add_u32 v30, v30, 4, v2
	v_lshl_add_u32 v6, v3, 4, v2
	s_addc_u32 s5, s96, s5
	v_mov_b32_e32 v2, v1
	v_mov_b32_e32 v3, v1
	v_lshl_add_u64 v[94:95], s[4:5], 0, v[0:1]
	v_mov_b32_e32 v0, v1
	v_add_u32_e32 v116, v8, v5
	v_add_u32_e32 v117, v9, v5
	v_add_u32_e32 v118, v18, v5
	v_add_u32_e32 v119, v19, v5
	v_add_u32_e32 v120, v20, v5
	v_add_u32_e32 v121, v21, v5
	v_add_u32_e32 v122, v22, v5
	v_add_u32_e32 v123, v23, v5
	v_add_u32_e32 v124, v24, v5
	v_add_u32_e32 v125, v25, v5
	v_add_u32_e32 v126, v26, v5
	v_add_u32_e32 v127, v27, v5
	v_add_u32_e32 v128, v28, v5
	v_add_u32_e32 v129, v29, v5
	v_add_u32_e32 v130, v30, v5
	v_add_u32_e32 v131, v6, v5
	v_add_u32_e32 v4, 0, v4
	v_add_u32_e32 v133, v10, v7
	v_add_u32_e32 v134, v10, v11
	v_add_u32_e32 v135, v10, v12
	v_add_u32_e32 v136, v10, v13
	v_add_u32_e32 v137, v10, v14
	v_add_u32_e32 v138, v10, v15
	v_add_u32_e32 v139, v10, v16
	v_add_u32_e32 v140, v10, v17
	v_mov_b64_e32 v[64:65], v[2:3]
	v_mov_b64_e32 v[60:61], v[2:3]
	v_mov_b64_e32 v[56:57], v[2:3]
	v_mov_b64_e32 v[52:53], v[2:3]
	v_mov_b64_e32 v[48:49], v[2:3]
	v_mov_b64_e32 v[44:45], v[2:3]
	v_mov_b64_e32 v[40:41], v[2:3]
	v_mov_b64_e32 v[36:37], v[2:3]
	v_mov_b64_e32 v[32:33], v[2:3]
	v_mov_b64_e32 v[28:29], v[2:3]
	v_mov_b64_e32 v[24:25], v[2:3]
	v_mov_b64_e32 v[20:21], v[2:3]
	v_mov_b64_e32 v[16:17], v[2:3]
	v_mov_b64_e32 v[12:13], v[2:3]
	v_mov_b64_e32 v[8:9], v[2:3]
	v_add_u32_e32 v132, 0x21000, v4
	v_mov_b64_e32 v[62:63], v[0:1]
	v_mov_b64_e32 v[58:59], v[0:1]
	v_mov_b64_e32 v[54:55], v[0:1]
	v_mov_b64_e32 v[50:51], v[0:1]
	v_mov_b64_e32 v[46:47], v[0:1]
	v_mov_b64_e32 v[42:43], v[0:1]
	v_mov_b64_e32 v[38:39], v[0:1]
	v_mov_b64_e32 v[34:35], v[0:1]
	v_mov_b64_e32 v[30:31], v[0:1]
	v_mov_b64_e32 v[26:27], v[0:1]
	v_mov_b64_e32 v[22:23], v[0:1]
	v_mov_b64_e32 v[18:19], v[0:1]
	v_mov_b64_e32 v[14:15], v[0:1]
	v_mov_b64_e32 v[10:11], v[0:1]
	v_mov_b64_e32 v[6:7], v[0:1]
	v_mov_b64_e32 v[4:5], v[2:3]
	s_mov_b32 s1, 0
	v_mov_b32_e32 v115, 0
	v_mov_b32_e32 v96, 0xf149f2ca
	v_mov_b64_e32 v[2:3], v[0:1]
	ds_read_b128 v[160:163], v132
	ds_read_b128 v[164:167], v132 offset:1024
	ds_read_b128 v[168:171], v132 offset:2048
	ds_read_b128 v[172:175], v132 offset:3072
	ds_read_b128 v[176:179], v132 offset:4096
	ds_read_b128 v[180:183], v132 offset:5120
	ds_read_b128 v[184:187], v132 offset:6144
	ds_read_b128 v[188:191], v132 offset:7168
	ds_read_b128 v[192:195], v132 offset:8192
	ds_read_b128 v[196:199], v132 offset:9216
	s_waitcnt lgkmcnt(0)
	s_branch .LBB0_3811
.LBB0_3810:
	ds_read_b64_tr_b16 v[224:225], v116
	ds_read_b64_tr_b16 v[226:227], v116 offset:8192
	ds_read_b64_tr_b16 v[228:229], v117
	ds_read_b64_tr_b16 v[230:231], v117 offset:8192
	ds_read_b64_tr_b16 v[232:233], v118
	ds_read_b64_tr_b16 v[234:235], v118 offset:8192
	ds_read_b64_tr_b16 v[236:237], v119
	ds_read_b64_tr_b16 v[238:239], v119 offset:8192
	ds_read_b64_tr_b16 v[240:241], v120
	ds_read_b64_tr_b16 v[242:243], v120 offset:8192
	ds_read_b64_tr_b16 v[244:245], v121
	ds_read_b64_tr_b16 v[246:247], v121 offset:8192
	v_sub_f32_e32 v0, v66, v96
	v_exp_f32_e32 v102, v0
	v_sub_f32_e32 v0, v70, v96
	v_exp_f32_e32 v103, v0
	v_sub_f32_e32 v0, v67, v96
	v_exp_f32_e32 v104, v0
	v_sub_f32_e32 v0, v71, v96
	v_exp_f32_e32 v105, v0
	v_sub_f32_e32 v0, v68, v96
	v_exp_f32_e32 v106, v0
	v_sub_f32_e32 v0, v72, v96
	v_exp_f32_e32 v107, v0
	v_sub_f32_e32 v0, v69, v96
	v_exp_f32_e32 v108, v0
	v_sub_f32_e32 v0, v73, v96
	v_exp_f32_e32 v109, v0
	v_cvt_pk_bf16_f32 v66, v102, v104
	v_cvt_pk_bf16_f32 v67, v106, v108
	v_cvt_pk_bf16_f32 v68, v103, v105
	v_cvt_pk_bf16_f32 v69, v107, v109
	v_pk_add_f32 v[102:103], v[102:103], v[104:105]
	v_pk_add_f32 v[104:105], v[106:107], v[108:109]
	v_add_f32_e64 v70, v102, v104
	v_add_f32_e64 v71, v103, v105
	v_add_f32_e32 v0, v70, v71
	v_add_f32_e32 v115, v115, v0
	s_waitcnt lgkmcnt(10)
	v_mfma_f32_16x16x32_bf16 v[62:65], v[224:227], v[66:69], v[62:65]
	ds_read_b64_tr_b16 v[224:225], v122
	ds_read_b64_tr_b16 v[226:227], v122 offset:8192
	s_waitcnt lgkmcnt(10)
	v_mfma_f32_16x16x32_bf16 v[58:61], v[228:231], v[66:69], v[58:61]
	ds_read_b64_tr_b16 v[228:229], v123
	ds_read_b64_tr_b16 v[230:231], v123 offset:8192
	s_waitcnt lgkmcnt(10)
	v_mfma_f32_16x16x32_bf16 v[54:57], v[232:235], v[66:69], v[54:57]
	ds_read_b64_tr_b16 v[232:233], v124
	ds_read_b64_tr_b16 v[234:235], v124 offset:8192
	s_waitcnt lgkmcnt(10)
	v_mfma_f32_16x16x32_bf16 v[50:53], v[236:239], v[66:69], v[50:53]
	ds_read_b64_tr_b16 v[236:237], v125
	ds_read_b64_tr_b16 v[238:239], v125 offset:8192
	s_waitcnt lgkmcnt(10)
	v_mfma_f32_16x16x32_bf16 v[46:49], v[240:243], v[66:69], v[46:49]
	ds_read_b64_tr_b16 v[240:241], v126
	ds_read_b64_tr_b16 v[242:243], v126 offset:8192
	s_waitcnt lgkmcnt(10)
	v_mfma_f32_16x16x32_bf16 v[42:45], v[244:247], v[66:69], v[42:45]
	ds_read_b64_tr_b16 v[244:245], v127
	ds_read_b64_tr_b16 v[246:247], v127 offset:8192
	s_waitcnt lgkmcnt(10)
	v_mfma_f32_16x16x32_bf16 v[38:41], v[224:227], v[66:69], v[38:41]
	ds_read_b64_tr_b16 v[224:225], v128
	ds_read_b64_tr_b16 v[226:227], v128 offset:8192
	s_waitcnt lgkmcnt(10)
	v_mfma_f32_16x16x32_bf16 v[34:37], v[228:231], v[66:69], v[34:37]
	ds_read_b64_tr_b16 v[228:229], v129
	ds_read_b64_tr_b16 v[230:231], v129 offset:8192
	s_waitcnt lgkmcnt(10)
	v_mfma_f32_16x16x32_bf16 v[30:33], v[232:235], v[66:69], v[30:33]
	ds_read_b64_tr_b16 v[232:233], v130
	ds_read_b64_tr_b16 v[234:235], v130 offset:8192
	s_waitcnt lgkmcnt(10)
	v_mfma_f32_16x16x32_bf16 v[26:29], v[236:239], v[66:69], v[26:29]
	ds_read_b64_tr_b16 v[236:237], v131
	ds_read_b64_tr_b16 v[238:239], v131 offset:8192
	s_waitcnt lgkmcnt(10)
	v_mfma_f32_16x16x32_bf16 v[22:25], v[240:243], v[66:69], v[22:25]
	s_waitcnt lgkmcnt(8)
	v_mfma_f32_16x16x32_bf16 v[18:21], v[244:247], v[66:69], v[18:21]
	s_waitcnt lgkmcnt(6)
	v_mfma_f32_16x16x32_bf16 v[14:17], v[224:227], v[66:69], v[14:17]
	s_waitcnt lgkmcnt(4)
	v_mfma_f32_16x16x32_bf16 v[10:13], v[228:231], v[66:69], v[10:13]
	s_waitcnt lgkmcnt(2)
	v_mfma_f32_16x16x32_bf16 v[6:9], v[232:235], v[66:69], v[6:9]
	s_waitcnt lgkmcnt(0)
	v_mfma_f32_16x16x32_bf16 v[2:5], v[236:239], v[66:69], v[2:5]
	s_mov_b64 s[8:9], 0x2800
	s_add_i32 s1, s1, 2
	v_lshl_add_u64 v[94:95], v[94:95], 0, s[8:9]
	s_and_b64 vcc, exec, s[4:5]
	s_cbranch_vccnz .LBB0_3815
.LBB0_3811:
	global_load_dwordx2 v[108:109], v[94:95], off offset:1024
	global_load_dwordx2 v[106:107], v[94:95], off offset:1536
	global_load_dwordx2 v[104:105], v[94:95], off offset:2048
	global_load_dwordx2 v[102:103], v[94:95], off offset:2560
	global_load_dwordx2 v[100:101], v[94:95], off offset:3072
	global_load_dwordx2 v[98:99], v[94:95], off offset:3584
	v_add_co_u32_e32 v66, vcc, s70, v94
	s_nop 1
	v_addc_co_u32_e32 v67, vcc, 0, v95, vcc
	global_load_dwordx2 v[112:113], v[94:95], off
	global_load_dwordx2 v[110:111], v[94:95], off offset:512
	global_load_dwordx2 v[72:73], v[66:67], off
	global_load_dwordx2 v[70:71], v[66:67], off offset:512
	s_waitcnt vmcnt(19)
	v_cvt_pk_f32_fp8_e32 v[208:209], v74
	v_cvt_pk_f32_fp8_sdwa v[210:211], v74 src0_sel:WORD_1
	v_cvt_pk_f32_fp8_e32 v[212:213], v75
	v_cvt_pk_f32_fp8_sdwa v[214:215], v75 src0_sel:WORD_1
	v_cvt_pk_bf16_f32 v200, v208, v209
	v_cvt_pk_bf16_f32 v201, v210, v211
	v_cvt_pk_bf16_f32 v202, v212, v213
	v_cvt_pk_bf16_f32 v203, v214, v215
	s_waitcnt vmcnt(18)
	v_cvt_pk_f32_fp8_e32 v[208:209], v76
	v_cvt_pk_f32_fp8_sdwa v[210:211], v76 src0_sel:WORD_1
	v_cvt_pk_f32_fp8_e32 v[212:213], v77
	v_cvt_pk_f32_fp8_sdwa v[214:215], v77 src0_sel:WORD_1
	v_cvt_pk_bf16_f32 v204, v208, v209
	v_cvt_pk_bf16_f32 v205, v210, v211
	v_cvt_pk_bf16_f32 v206, v212, v213
	v_cvt_pk_bf16_f32 v207, v214, v215
	v_mfma_f32_16x16x32_bf16 v[216:219], v[200:203], v[160:163], 0
	ds_write_b128 v133, v[200:203]
	s_waitcnt vmcnt(17)
	v_cvt_pk_f32_fp8_e32 v[208:209], v78
	v_cvt_pk_f32_fp8_sdwa v[210:211], v78 src0_sel:WORD_1
	v_cvt_pk_f32_fp8_e32 v[212:213], v79
	v_cvt_pk_f32_fp8_sdwa v[214:215], v79 src0_sel:WORD_1
	v_cvt_pk_bf16_f32 v200, v208, v209
	v_cvt_pk_bf16_f32 v201, v210, v211
	v_cvt_pk_bf16_f32 v202, v212, v213
	v_cvt_pk_bf16_f32 v203, v214, v215
	v_mfma_f32_16x16x32_bf16 v[216:219], v[204:207], v[164:167], v[216:219]
	ds_write_b128 v134, v[204:207]
	s_waitcnt vmcnt(16)
	v_cvt_pk_f32_fp8_e32 v[208:209], v80
	v_cvt_pk_f32_fp8_sdwa v[210:211], v80 src0_sel:WORD_1
	v_cvt_pk_f32_fp8_e32 v[212:213], v81
	v_cvt_pk_f32_fp8_sdwa v[214:215], v81 src0_sel:WORD_1
	v_cvt_pk_bf16_f32 v204, v208, v209
	v_cvt_pk_bf16_f32 v205, v210, v211
	v_cvt_pk_bf16_f32 v206, v212, v213
	v_cvt_pk_bf16_f32 v207, v214, v215
	v_mfma_f32_16x16x32_bf16 v[216:219], v[200:203], v[168:171], v[216:219]
	ds_write_b128 v135, v[200:203]
	s_waitcnt vmcnt(15)
	v_cvt_pk_f32_fp8_e32 v[208:209], v82
	v_cvt_pk_f32_fp8_sdwa v[210:211], v82 src0_sel:WORD_1
	v_cvt_pk_f32_fp8_e32 v[212:213], v83
	v_cvt_pk_f32_fp8_sdwa v[214:215], v83 src0_sel:WORD_1
	v_cvt_pk_bf16_f32 v200, v208, v209
	v_cvt_pk_bf16_f32 v201, v210, v211
	v_cvt_pk_bf16_f32 v202, v212, v213
	v_cvt_pk_bf16_f32 v203, v214, v215
	v_mfma_f32_16x16x32_bf16 v[216:219], v[204:207], v[172:175], v[216:219]
	ds_write_b128 v136, v[204:207]
	s_waitcnt vmcnt(14)
	v_cvt_pk_f32_fp8_e32 v[208:209], v84
	v_cvt_pk_f32_fp8_sdwa v[210:211], v84 src0_sel:WORD_1
	v_cvt_pk_f32_fp8_e32 v[212:213], v85
	v_cvt_pk_f32_fp8_sdwa v[214:215], v85 src0_sel:WORD_1
	v_cvt_pk_bf16_f32 v204, v208, v209
	v_cvt_pk_bf16_f32 v205, v210, v211
	v_cvt_pk_bf16_f32 v206, v212, v213
	v_cvt_pk_bf16_f32 v207, v214, v215
	v_mfma_f32_16x16x32_bf16 v[216:219], v[200:203], v[176:179], v[216:219]
	ds_write_b128 v137, v[200:203]
	s_waitcnt vmcnt(13)
	v_cvt_pk_f32_fp8_e32 v[208:209], v86
	v_cvt_pk_f32_fp8_sdwa v[210:211], v86 src0_sel:WORD_1
	v_cvt_pk_f32_fp8_e32 v[212:213], v87
	v_cvt_pk_f32_fp8_sdwa v[214:215], v87 src0_sel:WORD_1
	v_cvt_pk_bf16_f32 v200, v208, v209
	v_cvt_pk_bf16_f32 v201, v210, v211
	v_cvt_pk_bf16_f32 v202, v212, v213
	v_cvt_pk_bf16_f32 v203, v214, v215
	v_mfma_f32_16x16x32_bf16 v[216:219], v[204:207], v[180:183], v[216:219]
	ds_write_b128 v138, v[204:207]
	s_waitcnt vmcnt(12)
	v_cvt_pk_f32_fp8_e32 v[208:209], v88
	v_cvt_pk_f32_fp8_sdwa v[210:211], v88 src0_sel:WORD_1
	v_cvt_pk_f32_fp8_e32 v[212:213], v89
	v_cvt_pk_f32_fp8_sdwa v[214:215], v89 src0_sel:WORD_1
	v_cvt_pk_bf16_f32 v204, v208, v209
	v_cvt_pk_bf16_f32 v205, v210, v211
	v_cvt_pk_bf16_f32 v206, v212, v213
	v_cvt_pk_bf16_f32 v207, v214, v215
	v_mfma_f32_16x16x32_bf16 v[216:219], v[200:203], v[184:187], v[216:219]
	ds_write_b128 v139, v[200:203]
	s_waitcnt vmcnt(11)
	v_cvt_pk_f32_fp8_e32 v[208:209], v90
	v_cvt_pk_f32_fp8_sdwa v[210:211], v90 src0_sel:WORD_1
	v_cvt_pk_f32_fp8_e32 v[212:213], v91
	v_cvt_pk_f32_fp8_sdwa v[214:215], v91 src0_sel:WORD_1
	v_cvt_pk_bf16_f32 v200, v208, v209
	v_cvt_pk_bf16_f32 v201, v210, v211
	v_cvt_pk_bf16_f32 v202, v212, v213
	v_cvt_pk_bf16_f32 v203, v214, v215
	v_mfma_f32_16x16x32_bf16 v[216:219], v[204:207], v[188:191], v[216:219]
	ds_write_b128 v140, v[204:207]
	s_waitcnt vmcnt(10)
	v_cvt_pk_f32_fp8_e32 v[208:209], v92
	v_cvt_pk_f32_fp8_sdwa v[210:211], v92 src0_sel:WORD_1
	v_cvt_pk_f32_fp8_e32 v[212:213], v93
	v_cvt_pk_f32_fp8_sdwa v[214:215], v93 src0_sel:WORD_1
	v_cvt_pk_bf16_f32 v204, v208, v209
	v_cvt_pk_bf16_f32 v205, v210, v211
	v_cvt_pk_bf16_f32 v206, v212, v213
	v_cvt_pk_bf16_f32 v207, v214, v215
	v_mfma_f32_16x16x32_bf16 v[216:219], v[200:203], v[192:195], v[216:219]
	s_nop 1
	v_mfma_f32_16x16x32_bf16 v[66:69], v[204:207], v[196:199], v[216:219]
	s_cmp_gt_u32 s1, 29
	s_cselect_b64 s[4:5], -1, 0
	s_and_b64 vcc, exec, s[4:5]
	s_cbranch_vccnz .LBB0_3813
	v_add_co_u32_e32 v84, vcc, 0x1000, v94
	s_nop 1
	v_addc_co_u32_e32 v85, vcc, 0, v95, vcc
	v_add_co_u32_e32 v92, vcc, 0x2000, v94
	global_load_dwordx2 v[74:75], v[84:85], off offset:1024
	global_load_dwordx2 v[76:77], v[84:85], off offset:1536
	global_load_dwordx2 v[78:79], v[84:85], off offset:2048
	global_load_dwordx2 v[80:81], v[84:85], off offset:2560
	v_addc_co_u32_e32 v93, vcc, 0, v95, vcc
	global_load_dwordx2 v[82:83], v[84:85], off offset:3072
	s_nop 0
	global_load_dwordx2 v[84:85], v[84:85], off offset:3584
	s_nop 0
	global_load_dwordx2 v[86:87], v[92:93], off
	global_load_dwordx2 v[88:89], v[92:93], off offset:512
	global_load_dwordx2 v[90:91], v[92:93], off offset:1024
	s_nop 0
	global_load_dwordx2 v[92:93], v[92:93], off offset:1536
	s_waitcnt vmcnt(13)
	v_cvt_pk_f32_fp8_e32 v[208:209], v112
	v_cvt_pk_f32_fp8_sdwa v[210:211], v112 src0_sel:WORD_1
	v_cvt_pk_f32_fp8_e32 v[212:213], v113
	v_cvt_pk_f32_fp8_sdwa v[214:215], v113 src0_sel:WORD_1
	v_cvt_pk_bf16_f32 v200, v208, v209
	v_cvt_pk_bf16_f32 v201, v210, v211
	v_cvt_pk_bf16_f32 v202, v212, v213
	v_cvt_pk_bf16_f32 v203, v214, v215
	s_waitcnt vmcnt(12)
	v_cvt_pk_f32_fp8_e32 v[208:209], v110
	v_cvt_pk_f32_fp8_sdwa v[210:211], v110 src0_sel:WORD_1
	v_cvt_pk_f32_fp8_e32 v[212:213], v111
	v_cvt_pk_f32_fp8_sdwa v[214:215], v111 src0_sel:WORD_1
	v_cvt_pk_bf16_f32 v204, v208, v209
	v_cvt_pk_bf16_f32 v205, v210, v211
	v_cvt_pk_bf16_f32 v206, v212, v213
	v_cvt_pk_bf16_f32 v207, v214, v215
	v_mfma_f32_16x16x32_bf16 v[220:223], v[200:203], v[160:163], 0
	ds_write_b128 v133, v[200:203] offset:8192
	v_cvt_pk_f32_fp8_e32 v[208:209], v108
	v_cvt_pk_f32_fp8_sdwa v[210:211], v108 src0_sel:WORD_1
	v_cvt_pk_f32_fp8_e32 v[212:213], v109
	v_cvt_pk_f32_fp8_sdwa v[214:215], v109 src0_sel:WORD_1
	v_cvt_pk_bf16_f32 v200, v208, v209
	v_cvt_pk_bf16_f32 v201, v210, v211
	v_cvt_pk_bf16_f32 v202, v212, v213
	v_cvt_pk_bf16_f32 v203, v214, v215
	v_mfma_f32_16x16x32_bf16 v[220:223], v[204:207], v[164:167], v[220:223]
	ds_write_b128 v134, v[204:207] offset:8192
	v_cvt_pk_f32_fp8_e32 v[208:209], v106
	v_cvt_pk_f32_fp8_sdwa v[210:211], v106 src0_sel:WORD_1
	v_cvt_pk_f32_fp8_e32 v[212:213], v107
	v_cvt_pk_f32_fp8_sdwa v[214:215], v107 src0_sel:WORD_1
	v_cvt_pk_bf16_f32 v204, v208, v209
	v_cvt_pk_bf16_f32 v205, v210, v211
	v_cvt_pk_bf16_f32 v206, v212, v213
	v_cvt_pk_bf16_f32 v207, v214, v215
	v_mfma_f32_16x16x32_bf16 v[220:223], v[200:203], v[168:171], v[220:223]
	ds_write_b128 v135, v[200:203] offset:8192
	v_cvt_pk_f32_fp8_e32 v[208:209], v104
	v_cvt_pk_f32_fp8_sdwa v[210:211], v104 src0_sel:WORD_1
	v_cvt_pk_f32_fp8_e32 v[212:213], v105
	v_cvt_pk_f32_fp8_sdwa v[214:215], v105 src0_sel:WORD_1
	v_cvt_pk_bf16_f32 v200, v208, v209
	v_cvt_pk_bf16_f32 v201, v210, v211
	v_cvt_pk_bf16_f32 v202, v212, v213
	v_cvt_pk_bf16_f32 v203, v214, v215
	v_mfma_f32_16x16x32_bf16 v[220:223], v[204:207], v[172:175], v[220:223]
	ds_write_b128 v136, v[204:207] offset:8192
	v_cvt_pk_f32_fp8_e32 v[208:209], v102
	v_cvt_pk_f32_fp8_sdwa v[210:211], v102 src0_sel:WORD_1
	v_cvt_pk_f32_fp8_e32 v[212:213], v103
	v_cvt_pk_f32_fp8_sdwa v[214:215], v103 src0_sel:WORD_1
	v_cvt_pk_bf16_f32 v204, v208, v209
	v_cvt_pk_bf16_f32 v205, v210, v211
	v_cvt_pk_bf16_f32 v206, v212, v213
	v_cvt_pk_bf16_f32 v207, v214, v215
	v_mfma_f32_16x16x32_bf16 v[220:223], v[200:203], v[176:179], v[220:223]
	ds_write_b128 v137, v[200:203] offset:8192
	v_cvt_pk_f32_fp8_e32 v[208:209], v100
	v_cvt_pk_f32_fp8_sdwa v[210:211], v100 src0_sel:WORD_1
	v_cvt_pk_f32_fp8_e32 v[212:213], v101
	v_cvt_pk_f32_fp8_sdwa v[214:215], v101 src0_sel:WORD_1
	v_cvt_pk_bf16_f32 v200, v208, v209
	v_cvt_pk_bf16_f32 v201, v210, v211
	v_cvt_pk_bf16_f32 v202, v212, v213
	v_cvt_pk_bf16_f32 v203, v214, v215
	v_mfma_f32_16x16x32_bf16 v[220:223], v[204:207], v[180:183], v[220:223]
	ds_write_b128 v138, v[204:207] offset:8192
	v_cvt_pk_f32_fp8_e32 v[208:209], v98
	v_cvt_pk_f32_fp8_sdwa v[210:211], v98 src0_sel:WORD_1
	v_cvt_pk_f32_fp8_e32 v[212:213], v99
	v_cvt_pk_f32_fp8_sdwa v[214:215], v99 src0_sel:WORD_1
	v_cvt_pk_bf16_f32 v204, v208, v209
	v_cvt_pk_bf16_f32 v205, v210, v211
	v_cvt_pk_bf16_f32 v206, v212, v213
	v_cvt_pk_bf16_f32 v207, v214, v215
	v_mfma_f32_16x16x32_bf16 v[220:223], v[200:203], v[184:187], v[220:223]
	ds_write_b128 v139, v[200:203] offset:8192
	s_waitcnt vmcnt(11)
	v_cvt_pk_f32_fp8_e32 v[208:209], v72
	v_cvt_pk_f32_fp8_sdwa v[210:211], v72 src0_sel:WORD_1
	v_cvt_pk_f32_fp8_e32 v[212:213], v73
	v_cvt_pk_f32_fp8_sdwa v[214:215], v73 src0_sel:WORD_1
	v_cvt_pk_bf16_f32 v200, v208, v209
	v_cvt_pk_bf16_f32 v201, v210, v211
	v_cvt_pk_bf16_f32 v202, v212, v213
	v_cvt_pk_bf16_f32 v203, v214, v215
	v_mfma_f32_16x16x32_bf16 v[220:223], v[204:207], v[188:191], v[220:223]
	ds_write_b128 v140, v[204:207] offset:8192
	s_waitcnt vmcnt(10)
	v_cvt_pk_f32_fp8_e32 v[208:209], v70
	v_cvt_pk_f32_fp8_sdwa v[210:211], v70 src0_sel:WORD_1
	v_cvt_pk_f32_fp8_e32 v[212:213], v71
	v_cvt_pk_f32_fp8_sdwa v[214:215], v71 src0_sel:WORD_1
	v_cvt_pk_bf16_f32 v204, v208, v209
	v_cvt_pk_bf16_f32 v205, v210, v211
	v_cvt_pk_bf16_f32 v206, v212, v213
	v_cvt_pk_bf16_f32 v207, v214, v215
	v_mfma_f32_16x16x32_bf16 v[220:223], v[200:203], v[192:195], v[220:223]
	s_nop 1
	v_mfma_f32_16x16x32_bf16 v[70:73], v[204:207], v[196:199], v[220:223]
	s_branch .Lmy_a3_join
.LBB0_3813:
	s_waitcnt vmcnt(3)
	v_cvt_pk_f32_fp8_e32 v[208:209], v112
	v_cvt_pk_f32_fp8_sdwa v[210:211], v112 src0_sel:WORD_1
	v_cvt_pk_f32_fp8_e32 v[212:213], v113
	v_cvt_pk_f32_fp8_sdwa v[214:215], v113 src0_sel:WORD_1
	v_cvt_pk_bf16_f32 v200, v208, v209
	v_cvt_pk_bf16_f32 v201, v210, v211
	v_cvt_pk_bf16_f32 v202, v212, v213
	v_cvt_pk_bf16_f32 v203, v214, v215
	s_waitcnt vmcnt(2)
	v_cvt_pk_f32_fp8_e32 v[208:209], v110
	v_cvt_pk_f32_fp8_sdwa v[210:211], v110 src0_sel:WORD_1
	v_cvt_pk_f32_fp8_e32 v[212:213], v111
	v_cvt_pk_f32_fp8_sdwa v[214:215], v111 src0_sel:WORD_1
	v_cvt_pk_bf16_f32 v204, v208, v209
	v_cvt_pk_bf16_f32 v205, v210, v211
	v_cvt_pk_bf16_f32 v206, v212, v213
	v_cvt_pk_bf16_f32 v207, v214, v215
	v_mfma_f32_16x16x32_bf16 v[220:223], v[200:203], v[160:163], 0
	ds_write_b128 v133, v[200:203] offset:8192
	v_cvt_pk_f32_fp8_e32 v[208:209], v108
	v_cvt_pk_f32_fp8_sdwa v[210:211], v108 src0_sel:WORD_1
	v_cvt_pk_f32_fp8_e32 v[212:213], v109
	v_cvt_pk_f32_fp8_sdwa v[214:215], v109 src0_sel:WORD_1
	v_cvt_pk_bf16_f32 v200, v208, v209
	v_cvt_pk_bf16_f32 v201, v210, v211
	v_cvt_pk_bf16_f32 v202, v212, v213
	v_cvt_pk_bf16_f32 v203, v214, v215
	v_mfma_f32_16x16x32_bf16 v[220:223], v[204:207], v[164:167], v[220:223]
	ds_write_b128 v134, v[204:207] offset:8192
	v_cvt_pk_f32_fp8_e32 v[208:209], v106
	v_cvt_pk_f32_fp8_sdwa v[210:211], v106 src0_sel:WORD_1
	v_cvt_pk_f32_fp8_e32 v[212:213], v107
	v_cvt_pk_f32_fp8_sdwa v[214:215], v107 src0_sel:WORD_1
	v_cvt_pk_bf16_f32 v204, v208, v209
	v_cvt_pk_bf16_f32 v205, v210, v211
	v_cvt_pk_bf16_f32 v206, v212, v213
	v_cvt_pk_bf16_f32 v207, v214, v215
	v_mfma_f32_16x16x32_bf16 v[220:223], v[200:203], v[168:171], v[220:223]
	ds_write_b128 v135, v[200:203] offset:8192
	v_cvt_pk_f32_fp8_e32 v[208:209], v104
	v_cvt_pk_f32_fp8_sdwa v[210:211], v104 src0_sel:WORD_1
	v_cvt_pk_f32_fp8_e32 v[212:213], v105
	v_cvt_pk_f32_fp8_sdwa v[214:215], v105 src0_sel:WORD_1
	v_cvt_pk_bf16_f32 v200, v208, v209
	v_cvt_pk_bf16_f32 v201, v210, v211
	v_cvt_pk_bf16_f32 v202, v212, v213
	v_cvt_pk_bf16_f32 v203, v214, v215
	v_mfma_f32_16x16x32_bf16 v[220:223], v[204:207], v[172:175], v[220:223]
	ds_write_b128 v136, v[204:207] offset:8192
	v_cvt_pk_f32_fp8_e32 v[208:209], v102
	v_cvt_pk_f32_fp8_sdwa v[210:211], v102 src0_sel:WORD_1
	v_cvt_pk_f32_fp8_e32 v[212:213], v103
	v_cvt_pk_f32_fp8_sdwa v[214:215], v103 src0_sel:WORD_1
	v_cvt_pk_bf16_f32 v204, v208, v209
	v_cvt_pk_bf16_f32 v205, v210, v211
	v_cvt_pk_bf16_f32 v206, v212, v213
	v_cvt_pk_bf16_f32 v207, v214, v215
	v_mfma_f32_16x16x32_bf16 v[220:223], v[200:203], v[176:179], v[220:223]
	ds_write_b128 v137, v[200:203] offset:8192
	v_cvt_pk_f32_fp8_e32 v[208:209], v100
	v_cvt_pk_f32_fp8_sdwa v[210:211], v100 src0_sel:WORD_1
	v_cvt_pk_f32_fp8_e32 v[212:213], v101
	v_cvt_pk_f32_fp8_sdwa v[214:215], v101 src0_sel:WORD_1
	v_cvt_pk_bf16_f32 v200, v208, v209
	v_cvt_pk_bf16_f32 v201, v210, v211
	v_cvt_pk_bf16_f32 v202, v212, v213
	v_cvt_pk_bf16_f32 v203, v214, v215
	v_mfma_f32_16x16x32_bf16 v[220:223], v[204:207], v[180:183], v[220:223]
	ds_write_b128 v138, v[204:207] offset:8192
	v_cvt_pk_f32_fp8_e32 v[208:209], v98
	v_cvt_pk_f32_fp8_sdwa v[210:211], v98 src0_sel:WORD_1
	v_cvt_pk_f32_fp8_e32 v[212:213], v99
	v_cvt_pk_f32_fp8_sdwa v[214:215], v99 src0_sel:WORD_1
	v_cvt_pk_bf16_f32 v204, v208, v209
	v_cvt_pk_bf16_f32 v205, v210, v211
	v_cvt_pk_bf16_f32 v206, v212, v213
	v_cvt_pk_bf16_f32 v207, v214, v215
	v_mfma_f32_16x16x32_bf16 v[220:223], v[200:203], v[184:187], v[220:223]
	ds_write_b128 v139, v[200:203] offset:8192
	s_waitcnt vmcnt(1)
	v_cvt_pk_f32_fp8_e32 v[208:209], v72
	v_cvt_pk_f32_fp8_sdwa v[210:211], v72 src0_sel:WORD_1
	v_cvt_pk_f32_fp8_e32 v[212:213], v73
	v_cvt_pk_f32_fp8_sdwa v[214:215], v73 src0_sel:WORD_1
	v_cvt_pk_bf16_f32 v200, v208, v209
	v_cvt_pk_bf16_f32 v201, v210, v211
	v_cvt_pk_bf16_f32 v202, v212, v213
	v_cvt_pk_bf16_f32 v203, v214, v215
	v_mfma_f32_16x16x32_bf16 v[220:223], v[204:207], v[188:191], v[220:223]
	ds_write_b128 v140, v[204:207] offset:8192
	s_waitcnt vmcnt(0)
	v_cvt_pk_f32_fp8_e32 v[208:209], v70
	v_cvt_pk_f32_fp8_sdwa v[210:211], v70 src0_sel:WORD_1
	v_cvt_pk_f32_fp8_e32 v[212:213], v71
	v_cvt_pk_f32_fp8_sdwa v[214:215], v71 src0_sel:WORD_1
	v_cvt_pk_bf16_f32 v204, v208, v209
	v_cvt_pk_bf16_f32 v205, v210, v211
	v_cvt_pk_bf16_f32 v206, v212, v213
	v_cvt_pk_bf16_f32 v207, v214, v215
	v_mfma_f32_16x16x32_bf16 v[220:223], v[200:203], v[192:195], v[220:223]
	s_nop 1
	v_mfma_f32_16x16x32_bf16 v[70:73], v[204:207], v[196:199], v[220:223]
.Lmy_a3_join:
	v_max_f32_e32 v0, v67, v67
	s_nop 1
	v_max_f32_e32 v98, v66, v66
	v_max_f32_e32 v0, v98, v0
	v_max_f32_e32 v98, v69, v69
	v_max_f32_e32 v99, v68, v68
	v_max_f32_e32 v98, v99, v98
	v_max_f32_e32 v99, v73, v73
	v_max_f32_e32 v100, v72, v72
	v_max_f32_e32 v99, v100, v99
	v_max3_f32 v99, v70, v71, v99
	v_max3_f32 v0, v0, v98, v99
	ds_bpermute_b32 v98, v114, v0
	s_waitcnt lgkmcnt(0)
	v_max_f32_e32 v98, v98, v98
	v_max_f32_e32 v0, v0, v98
	ds_bpermute_b32 v98, v97, v0
	s_waitcnt lgkmcnt(0)
	v_max_f32_e32 v98, v98, v98
	v_max_f32_e32 v0, v0, v98
	v_add_f32_e32 v98, 0x41000000, v96
	v_cmp_gt_f32_e32 vcc, v0, v98
	s_cbranch_vccz .LBB0_3810
	v_max_f32_e32 v0, v0, v0
	v_max_f32_e32 v98, v96, v96
	v_max_f32_e32 v98, v98, v0
	v_sub_f32_e32 v0, v96, v98
	v_exp_f32_e32 v0, v0
	v_mov_b32_e32 v96, v98
	v_pk_mul_f32 v[64:65], v[64:65], v[0:1] op_sel_hi:[1,0]
	v_pk_mul_f32 v[62:63], v[62:63], v[0:1] op_sel_hi:[1,0]
	v_pk_mul_f32 v[60:61], v[60:61], v[0:1] op_sel_hi:[1,0]
	v_pk_mul_f32 v[58:59], v[58:59], v[0:1] op_sel_hi:[1,0]
	v_pk_mul_f32 v[56:57], v[56:57], v[0:1] op_sel_hi:[1,0]
	v_pk_mul_f32 v[54:55], v[54:55], v[0:1] op_sel_hi:[1,0]
	v_pk_mul_f32 v[52:53], v[52:53], v[0:1] op_sel_hi:[1,0]
	v_pk_mul_f32 v[50:51], v[50:51], v[0:1] op_sel_hi:[1,0]
	v_pk_mul_f32 v[48:49], v[48:49], v[0:1] op_sel_hi:[1,0]
	v_pk_mul_f32 v[46:47], v[46:47], v[0:1] op_sel_hi:[1,0]
	v_pk_mul_f32 v[44:45], v[44:45], v[0:1] op_sel_hi:[1,0]
	v_pk_mul_f32 v[42:43], v[42:43], v[0:1] op_sel_hi:[1,0]
	v_pk_mul_f32 v[40:41], v[40:41], v[0:1] op_sel_hi:[1,0]
	v_pk_mul_f32 v[38:39], v[38:39], v[0:1] op_sel_hi:[1,0]
	v_pk_mul_f32 v[36:37], v[36:37], v[0:1] op_sel_hi:[1,0]
	v_pk_mul_f32 v[34:35], v[34:35], v[0:1] op_sel_hi:[1,0]
	v_pk_mul_f32 v[32:33], v[32:33], v[0:1] op_sel_hi:[1,0]
	v_pk_mul_f32 v[30:31], v[30:31], v[0:1] op_sel_hi:[1,0]
	v_pk_mul_f32 v[28:29], v[28:29], v[0:1] op_sel_hi:[1,0]
	v_pk_mul_f32 v[26:27], v[26:27], v[0:1] op_sel_hi:[1,0]
	v_pk_mul_f32 v[24:25], v[24:25], v[0:1] op_sel_hi:[1,0]
	v_pk_mul_f32 v[22:23], v[22:23], v[0:1] op_sel_hi:[1,0]
	v_pk_mul_f32 v[20:21], v[20:21], v[0:1] op_sel_hi:[1,0]
	v_pk_mul_f32 v[18:19], v[18:19], v[0:1] op_sel_hi:[1,0]
	v_pk_mul_f32 v[16:17], v[16:17], v[0:1] op_sel_hi:[1,0]
	v_pk_mul_f32 v[14:15], v[14:15], v[0:1] op_sel_hi:[1,0]
	v_pk_mul_f32 v[12:13], v[12:13], v[0:1] op_sel_hi:[1,0]
	v_pk_mul_f32 v[10:11], v[10:11], v[0:1] op_sel_hi:[1,0]
	v_pk_mul_f32 v[8:9], v[8:9], v[0:1] op_sel_hi:[1,0]
	v_pk_mul_f32 v[6:7], v[6:7], v[0:1] op_sel_hi:[1,0]
	v_pk_mul_f32 v[4:5], v[4:5], v[0:1] op_sel_hi:[1,0]
	v_pk_mul_f32 v[2:3], v[2:3], v[0:1] op_sel_hi:[1,0]
	v_mul_f32_e32 v115, v115, v0
	s_branch .LBB0_3810
